# work-queue tails: phase 6 serves the 8 small cmp2 items first instead of last, phase 5 serves SWA items before the smaller expand items (bijective index remaps) + cbias loads de-serialised
# speedup vs baseline: 1.0039x; 1.0003x over previous
.LBB0_420:
	s_or_b64 exec, exec, s[0:1]
	s_waitcnt lgkmcnt(0)
	s_barrier
	ds_read_b32 v0, v223
	s_movk_i32 s0, 0x87
	s_waitcnt lgkmcnt(0)
	v_cmp_lt_i32_e32 vcc, s0, v0
	v_readfirstlane_b32 s18, v0
	s_mov_b64 s[0:1], -1
	s_cbranch_vccnz .LBB0_415
	s_add_i32 s98, s18, 0x80
	s_sub_i32 s99, s18, 8
	s_cmp_lt_u32 s18, 8
	s_cselect_b32 s18, s98, s99
	s_cmpk_gt_i32 s18, 0x7f
	s_cbranch_scc0 .LBB0_472
	v_readlane_b32 s0, v250, 4
	s_add_i32 s14, s0, s18
	s_lshr_b32 s80, s14, 5
	s_lshl_b32 s0, s14, 7
	s_and_b32 s16, s0, 0xf80
	s_lshl_b64 s[0:1], s[80:81], 20
	v_mov_b32_e32 v213, v222
	v_mov_b32_e32 v215, v222
	s_add_u32 s0, s30, s0
	v_mov_b32_e32 v52, v222
	s_addc_u32 s1, s31, s1
	s_lshl_b32 s4, s16, 8
	s_add_u32 s0, s0, s4
	v_ashrrev_i32_e32 v34, 3, v52
	v_ashrrev_i32_e32 v35, 31, v34
	s_addc_u32 s1, s1, 0
	s_lshl_b64 s[4:5], s[80:81], 15
	v_lshlrev_b64 v[2:3], 8, v[34:35]
	v_lshlrev_b32_e32 v0, 4, v52
	s_add_u32 s4, s34, s4
	v_lshl_add_u64 v[4:5], s[0:1], 0, v[2:3]
	v_and_b32_e32 v0, 0x70, v0
	s_addc_u32 s5, s35, s5
	v_lshl_add_u64 v[36:37], v[4:5], 0, v[0:1]
	v_lshl_add_u64 v[2:3], s[4:5], 0, v[2:3]
	v_add_co_u32_e32 v40, vcc, s57, v36
	v_lshl_add_u64 v[38:39], v[2:3], 0, v[0:1]
	s_nop 0
	v_addc_co_u32_e32 v41, vcc, 0, v37, vcc
	v_add_co_u32_e32 v42, vcc, s57, v38
	s_nop 1
	v_addc_co_u32_e32 v43, vcc, 0, v39, vcc
	v_add_co_u32_e32 v44, vcc, s62, v36
	s_barrier
	s_nop 0
	v_addc_co_u32_e32 v45, vcc, 0, v37, vcc
	v_add_co_u32_e32 v46, vcc, s62, v38
	global_load_dwordx4 v[2:5], v[36:37], off
	global_load_dwordx4 v[6:9], v[38:39], off
	v_addc_co_u32_e32 v47, vcc, 0, v39, vcc
	global_load_dwordx4 v[10:13], v[40:41], off
	global_load_dwordx4 v[14:17], v[42:43], off
	v_add_co_u32_e32 v48, vcc, s88, v36
	global_load_dwordx4 v[18:21], v[44:45], off
	global_load_dwordx4 v[22:25], v[46:47], off
	v_addc_co_u32_e32 v49, vcc, 0, v37, vcc
	global_load_dwordx4 v[26:29], v[48:49], off
	v_add_co_u32_e32 v50, vcc, s88, v38
	v_lshrrev_b32_e32 v35, 1, v52
	s_nop 0
	v_addc_co_u32_e32 v51, vcc, 0, v39, vcc
	global_load_dwordx4 v[30:33], v[50:51], off
	global_load_dwordx4 v[178:181], v[36:37], off offset:128
	global_load_dwordx4 v[182:185], v[38:39], off offset:128
	global_load_dwordx4 v[186:189], v[40:41], off offset:128
	global_load_dwordx4 v[190:193], v[42:43], off offset:128
	global_load_dwordx4 v[194:197], v[44:45], off offset:128
	global_load_dwordx4 v[198:201], v[46:47], off offset:128
	global_load_dwordx4 v[202:205], v[48:49], off offset:128
	global_load_dwordx4 v[206:209], v[50:51], off offset:128
	v_and_b32_e32 v36, 31, v52
	s_mov_b32 s0, 0xfffffc0
	v_and_b32_e32 v37, 0x5f, v52
	v_and_or_b32 v38, v35, s0, v36
	v_and_b32_e32 v36, 16, v35
	v_mad_u64_u32 v[216:217], s[0:1], v38, s56, v[36:37]
	v_mad_u64_u32 v[218:219], s[0:1], v34, s56, v[0:1]
	v_mad_u32_u24 v217, v37, s56, v36
	s_cmp_gt_u32 s14, 31
	s_cselect_b64 s[0:1], -1, 0
	s_mov_b64 s[4:5], -1
	s_and_b64 vcc, exec, s[0:1]
	s_waitcnt vmcnt(15)
	ds_write_b128 v218, v[2:5]
	s_waitcnt vmcnt(13)
	ds_write_b128 v218, v[10:13] offset:4608
	s_waitcnt vmcnt(11)
	ds_write_b128 v218, v[18:21] offset:9216
	s_waitcnt vmcnt(9)
	ds_write_b128 v218, v[26:29] offset:13824
	ds_write_b128 v218, v[6:9] offset:36864
	ds_write_b128 v218, v[14:17] offset:41472
	ds_write_b128 v218, v[22:25] offset:46080
	s_waitcnt vmcnt(8)
	ds_write_b128 v218, v[30:33] offset:50688
	s_waitcnt lgkmcnt(0)
	s_barrier
	ds_read_b128 v[54:57], v216
	ds_read_b128 v[50:53], v216 offset:4608
	ds_read_b128 v[58:61], v217 offset:36864
	ds_read_b128 v[62:65], v217 offset:41472
	s_cbranch_vccz .LBB0_424
	s_waitcnt lgkmcnt(1)
	v_mfma_f32_32x32x16_bf16 v[2:17], v[54:57], v[58:61], 0
	s_mov_b64 s[4:5], 0
	s_waitcnt lgkmcnt(0)
	v_mfma_f32_32x32x16_bf16 v[18:33], v[54:57], v[62:65], 0
	v_mfma_f32_32x32x16_bf16 v[34:49], v[50:53], v[58:61], 0
	v_mfma_f32_32x32x16_bf16 v[82:97], v[50:53], v[62:65], 0

.LBB0_511:
	s_or_b64 exec, exec, s[0:1]
	s_waitcnt lgkmcnt(0)
	s_barrier
	ds_read_b32 v0, v223
	s_movk_i32 s0, 0x2c7
	s_waitcnt lgkmcnt(0)
	v_cmp_lt_i32_e32 vcc, s0, v0
	v_readfirstlane_b32 s51, v0
	s_mov_b64 s[0:1], -1
	s_cbranch_vccnz .LBB0_506
	s_add_i32 s98, s51, 0x1c0
	s_sub_i32 s99, s51, 0x100
	s_cmp_lt_u32 s51, 0x108
	s_cselect_b32 s98, s98, s99
	s_cmp_lt_u32 s51, 8
	s_cselect_b32 s51, s51, s98
	s_cmp_gt_i32 s51, 7
	s_cbranch_scc0 .LBB0_613
	s_cmpk_gt_u32 s51, 0xc7
	s_cbranch_scc0 .LBB0_590
	s_cmpk_gt_u32 s51, 0x1c7
	s_cbranch_scc0 .LBB0_538
	s_and_b32 s0, s51, 3
	v_readlane_b32 s1, v250, 8
	s_or_b32 s26, s0, s1
	s_mul_i32 s0, s26, 0x210
	v_mov_b32_e32 v0, v222
	v_mov_b32_e32 v2, v222
	s_add_u32 s0, s36, s0
	v_mov_b32_e32 v3, v222
	s_movk_i32 s4, 0x81
	s_addc_u32 s1, s37, 0
	s_barrier
	s_nop 0
	v_cmp_gt_i32_e32 vcc, s4, v3
	s_and_saveexec_b64 s[4:5], vcc
	s_cbranch_execz .LBB0_517
	v_mov_b32_e32 v4, v222
	s_nop 0
	v_ashrrev_i32_e32 v5, 31, v4
	v_lshl_add_u64 v[4:5], v[4:5], 2, s[0:1]
	global_load_dword v3, v[4:5], off
	v_mov_b32_e32 v4, v222
	s_nop 0
	v_lshlrev_b32_e32 v4, 2, v4
	s_waitcnt vmcnt(0)
	ds_write_b32 v4, v3 offset:60000
